# prologue: x->bf16 loop with 8 loads in flight and row-scale values prefetched with the weight loads in the transposes (plus lean GEMM load segments)
# speedup vs baseline: 1.0106x; 1.0106x over previous
.LBB0_476:
	s_andn2_b64 vcc, exec, s[6:7]
	s_cbranch_vccnz .LBB0_542
	s_mov_b32 s80, s75
	s_mul_i32 s6, s14, 0x5800000
	v_readlane_b32 s72, v254, 45
	s_mul_hi_i32 s7, s14, 0x5800000
	v_readlane_b32 s73, v254, 46
	s_add_u32 s6, s72, s6
	s_addc_u32 s7, s73, s7
	s_lshl_b32 s16, s14, 11
	s_ashr_i32 s17, s16, 31
	s_lshl_b64 s[16:17], s[16:17], 2
	s_add_u32 s16, s70, s16
	s_addc_u32 s17, s71, s17
	s_add_i32 s20, s18, 0xc000
	s_and_b32 s21, s20, 0xffff
	s_mul_i32 s21, s21, 0xba2f
	s_lshr_b32 s31, s21, 24
	s_mul_i32 s21, s31, 0x160
	s_sub_i32 s21, s20, s21
	s_lshl_b32 s31, s31, 6
	s_lshl_b32 s20, s21, 5
	s_and_b32 s20, s20, 0xffe0
	v_or_b32_e32 v34, s31, v66
	v_or_b32_e32 v0, s20, v68
	v_mul_u32_u24_e32 v1, 0x2c00, v34
	v_add_lshl_u32 v64, v0, v1, 2
	v_lshl_add_u64 v[32:33], s[6:7], 0, v[64:65]
	global_load_dword v0, v64, s[6:7]
	s_mov_b32 s6, 0x16000
	v_add_co_u32_e32 v2, vcc, s6, v32
	s_mov_b32 s6, 0x42000
	s_nop 0
	v_addc_co_u32_e32 v3, vcc, 0, v33, vcc
	global_load_dword v1, v[2:3], off
	v_add_co_u32_e32 v2, vcc, s49, v32
	v_readlane_b32 s74, v254, 47
	s_nop 0
	v_addc_co_u32_e32 v3, vcc, 0, v33, vcc
	v_add_co_u32_e32 v4, vcc, s6, v32
	global_load_dword v2, v[2:3], off
	s_nop 0
	v_addc_co_u32_e32 v5, vcc, 0, v33, vcc
	global_load_dword v3, v[4:5], off
	v_add_co_u32_e32 v4, vcc, s65, v32
	s_mov_b32 s6, 0x6e000
	s_nop 0
	v_addc_co_u32_e32 v5, vcc, 0, v33, vcc
	v_add_co_u32_e32 v6, vcc, s6, v32
	s_mov_b32 s6, 0x84000
	s_nop 0
	v_addc_co_u32_e32 v7, vcc, 0, v33, vcc
	global_load_dword v4, v[4:5], off
	v_readlane_b32 s75, v254, 48
	global_load_dword v5, v[6:7], off
	v_add_co_u32_e32 v6, vcc, s6, v32
	s_mov_b32 s6, 0x9a000
	s_nop 0
	v_addc_co_u32_e32 v7, vcc, 0, v33, vcc
	v_add_co_u32_e32 v8, vcc, s6, v32
	s_mov_b32 s6, 0xb0000
	s_nop 0
	v_addc_co_u32_e32 v9, vcc, 0, v33, vcc
	global_load_dword v6, v[6:7], off
	v_readlane_b32 s76, v254, 49
	global_load_dword v7, v[8:9], off
	v_add_co_u32_e32 v8, vcc, s6, v32
	s_mov_b32 s6, 0xc6000
	s_nop 0
	v_addc_co_u32_e32 v9, vcc, 0, v33, vcc
	v_add_co_u32_e32 v10, vcc, s6, v32
	s_mov_b32 s6, 0xdc000
	s_nop 0
	v_addc_co_u32_e32 v11, vcc, 0, v33, vcc
	global_load_dword v8, v[8:9], off
	v_readlane_b32 s77, v254, 50
	global_load_dword v9, v[10:11], off
	v_add_co_u32_e32 v10, vcc, s6, v32
	s_mov_b32 s6, 0xf2000
	s_nop 0
	v_addc_co_u32_e32 v11, vcc, 0, v33, vcc
	v_add_co_u32_e32 v12, vcc, s6, v32
	s_mov_b32 s6, 0x108000
	s_nop 0
	v_addc_co_u32_e32 v13, vcc, 0, v33, vcc
	global_load_dword v10, v[10:11], off
	v_readlane_b32 s78, v254, 51
	global_load_dword v11, v[12:13], off
	v_add_co_u32_e32 v12, vcc, s6, v32
	s_mov_b32 s6, 0x11e000
	s_nop 0
	v_addc_co_u32_e32 v13, vcc, 0, v33, vcc
	v_add_co_u32_e32 v14, vcc, s6, v32
	s_mov_b32 s6, 0x134000
	s_nop 0
	v_addc_co_u32_e32 v15, vcc, 0, v33, vcc
	global_load_dword v12, v[12:13], off
	v_readlane_b32 s79, v254, 52
	global_load_dword v13, v[14:15], off
	v_add_co_u32_e32 v14, vcc, s6, v32
	s_mov_b32 s6, 0x14a000
	s_nop 0
	v_addc_co_u32_e32 v15, vcc, 0, v33, vcc
	v_add_co_u32_e32 v16, vcc, s6, v32
	s_mov_b32 s6, 0x160000
	s_nop 0
	v_addc_co_u32_e32 v17, vcc, 0, v33, vcc
	global_load_dword v14, v[14:15], off
	s_nop 0
	global_load_dword v15, v[16:17], off
	v_add_co_u32_e32 v16, vcc, s6, v32
	s_mov_b32 s6, 0x176000
	s_nop 0
	v_addc_co_u32_e32 v17, vcc, 0, v33, vcc
	v_add_co_u32_e32 v18, vcc, s6, v32
	s_mov_b32 s6, 0x18c000
	s_nop 0
	v_addc_co_u32_e32 v19, vcc, 0, v33, vcc
	global_load_dword v16, v[16:17], off
	s_nop 0
	global_load_dword v17, v[18:19], off
	v_add_co_u32_e32 v18, vcc, s6, v32
	s_mov_b32 s6, 0x1a2000
	s_nop 0
	v_addc_co_u32_e32 v19, vcc, 0, v33, vcc
	v_add_co_u32_e32 v20, vcc, s6, v32
	s_mov_b32 s6, 0x1b8000
	s_nop 0
	v_addc_co_u32_e32 v21, vcc, 0, v33, vcc
	global_load_dword v18, v[18:19], off
	s_nop 0
	global_load_dword v19, v[20:21], off
	v_add_co_u32_e32 v20, vcc, s6, v32
	s_mov_b32 s6, 0x1ce000
	s_nop 0
	v_addc_co_u32_e32 v21, vcc, 0, v33, vcc
	v_add_co_u32_e32 v22, vcc, s6, v32
	s_mov_b32 s6, 0x1e4000
	s_nop 0
	v_addc_co_u32_e32 v23, vcc, 0, v33, vcc
	global_load_dword v20, v[20:21], off
	s_nop 0
	global_load_dword v21, v[22:23], off
	v_add_co_u32_e32 v22, vcc, s6, v32
	s_mov_b32 s6, 0x1fa000
	s_nop 0
	v_addc_co_u32_e32 v23, vcc, 0, v33, vcc
	v_add_co_u32_e32 v24, vcc, s6, v32
	global_load_dword v22, v[22:23], off
	s_nop 0
	v_addc_co_u32_e32 v25, vcc, 0, v33, vcc
	global_load_dword v23, v[24:25], off
	v_add_co_u32_e32 v24, vcc, s45, v32
	s_mov_b32 s6, 0x226000
	s_nop 0
	v_addc_co_u32_e32 v25, vcc, 0, v33, vcc
	v_add_co_u32_e32 v26, vcc, s6, v32
	s_mov_b32 s6, 0x23c000
	s_nop 0
	v_addc_co_u32_e32 v27, vcc, 0, v33, vcc
	global_load_dword v24, v[24:25], off
	s_nop 0
	global_load_dword v25, v[26:27], off
	v_add_co_u32_e32 v26, vcc, s6, v32
	s_mov_b32 s6, 0x252000
	s_nop 0
	v_addc_co_u32_e32 v27, vcc, 0, v33, vcc
	v_add_co_u32_e32 v28, vcc, s6, v32
	s_mov_b32 s6, 0x268000
	s_nop 0
	v_addc_co_u32_e32 v29, vcc, 0, v33, vcc
	global_load_dword v26, v[26:27], off
	s_nop 0
	global_load_dword v27, v[28:29], off
	v_add_co_u32_e32 v28, vcc, s6, v32
	s_nop 1
	v_addc_co_u32_e32 v29, vcc, 0, v33, vcc
	v_add_co_u32_e32 v30, vcc, 0x27e000, v32
	global_load_dword v28, v[28:29], off
	s_nop 0
	v_addc_co_u32_e32 v31, vcc, 0, v33, vcc
	global_load_dword v29, v[30:31], off
	v_add_co_u32_e32 v30, vcc, 0x294000, v32
	s_nop 1
	v_addc_co_u32_e32 v31, vcc, 0, v33, vcc
	v_add_co_u32_e32 v32, vcc, 0x2aa000, v32
	global_load_dword v30, v[30:31], off
	s_nop 0
	v_addc_co_u32_e32 v33, vcc, 0, v33, vcc
	global_load_dword v31, v[32:33], off
	v_cndmask_b32_e64 v32, 0, 1, s[10:11]
	v_cmp_ne_u32_e64 s[6:7], 1, v32
	s_andn2_b64 vcc, exec, s[10:11]
	s_cbranch_vccnz .Lgkpf_skip_gu
	v_add_lshl_u32 v132, v66, s31, 2
	global_load_dword v100, v132, s[16:17]
	global_load_dword v101, v132, s[16:17] offset:8
	global_load_dword v102, v132, s[16:17] offset:16
	global_load_dword v103, v132, s[16:17] offset:24
	global_load_dword v104, v132, s[16:17] offset:32
	global_load_dword v105, v132, s[16:17] offset:40
	global_load_dword v106, v132, s[16:17] offset:48
	global_load_dword v107, v132, s[16:17] offset:56
	global_load_dword v108, v132, s[16:17] offset:64
	global_load_dword v109, v132, s[16:17] offset:72
	global_load_dword v110, v132, s[16:17] offset:80
	global_load_dword v111, v132, s[16:17] offset:88
	global_load_dword v112, v132, s[16:17] offset:96
	global_load_dword v113, v132, s[16:17] offset:104
	global_load_dword v114, v132, s[16:17] offset:112
	global_load_dword v115, v132, s[16:17] offset:120
	global_load_dword v116, v132, s[16:17] offset:128
	global_load_dword v117, v132, s[16:17] offset:136
	global_load_dword v118, v132, s[16:17] offset:144
	global_load_dword v119, v132, s[16:17] offset:152
	global_load_dword v120, v132, s[16:17] offset:160
	global_load_dword v121, v132, s[16:17] offset:168
	global_load_dword v122, v132, s[16:17] offset:176
	global_load_dword v123, v132, s[16:17] offset:184
	global_load_dword v124, v132, s[16:17] offset:192
	global_load_dword v125, v132, s[16:17] offset:200
	global_load_dword v126, v132, s[16:17] offset:208
	global_load_dword v127, v132, s[16:17] offset:216
	global_load_dword v128, v132, s[16:17] offset:224
	global_load_dword v129, v132, s[16:17] offset:232
	global_load_dword v130, v132, s[16:17] offset:240
	global_load_dword v131, v132, s[16:17] offset:248
.Lgkpf_skip_gu:
	s_andn2_b64 vcc, exec, s[10:11]
	s_cbranch_vccnz .LBB0_479
	s_waitcnt vmcnt(0)
	v_mul_f32_e32 v0, v0, v100
.LBB0_479:
	s_waitcnt vmcnt(0)
	ds_write_b32 v71, v0
	s_and_b64 vcc, exec, s[6:7]
	v_add_lshl_u32 v0, v66, s31, 2
	s_mov_b32 s75, s80
	s_movk_i32 s78, 0x2000
	s_cbranch_vccnz .LBB0_481
	s_waitcnt vmcnt(0)
	v_mul_f32_e32 v1, v1, v101
.LBB0_481:
	v_add_u32_e32 v32, v69, v77
	s_and_b64 vcc, exec, s[6:7]
	ds_write_b32 v32, v1
	s_cbranch_vccnz .LBB0_483
	s_waitcnt vmcnt(0)
	v_mul_f32_e32 v2, v2, v102
.LBB0_483:
	v_add_u32_e32 v1, v69, v78
	s_and_b64 vcc, exec, s[6:7]
	ds_write_b32 v1, v2
	s_cbranch_vccnz .LBB0_485
	s_waitcnt vmcnt(0)
	v_mul_f32_e32 v3, v3, v103
.LBB0_485:
	v_add_u32_e32 v1, v69, v79
	s_and_b64 vcc, exec, s[6:7]
	ds_write_b32 v1, v3
	s_cbranch_vccnz .LBB0_487
	s_waitcnt vmcnt(0)
	v_mul_f32_e32 v4, v4, v104
.LBB0_487:
	v_add_u32_e32 v1, v69, v80
	s_and_b64 vcc, exec, s[6:7]
	ds_write_b32 v1, v4
	s_cbranch_vccnz .LBB0_489
	s_waitcnt vmcnt(0)
	v_mul_f32_e32 v5, v5, v105
.LBB0_489:
	v_add_u32_e32 v1, v69, v81
	s_and_b64 vcc, exec, s[6:7]
	ds_write_b32 v1, v5
	s_cbranch_vccnz .LBB0_491
	s_waitcnt vmcnt(0)
	v_mul_f32_e32 v6, v6, v106
.LBB0_491:
	v_add_u32_e32 v1, v69, v82
	s_and_b64 vcc, exec, s[6:7]
	ds_write_b32 v1, v6
	s_cbranch_vccnz .LBB0_493
	s_waitcnt vmcnt(0)
	v_mul_f32_e32 v7, v7, v107
.LBB0_493:
	v_add_u32_e32 v1, v69, v83
	s_and_b64 vcc, exec, s[6:7]
	ds_write_b32 v1, v7
	s_cbranch_vccnz .LBB0_495
	s_waitcnt vmcnt(0)
	v_mul_f32_e32 v8, v8, v108
.LBB0_495:
	v_add_u32_e32 v1, v69, v84
	s_and_b64 vcc, exec, s[6:7]
	ds_write_b32 v1, v8
	s_cbranch_vccnz .LBB0_497
	s_waitcnt vmcnt(0)
	v_mul_f32_e32 v9, v9, v109
.LBB0_497:
	v_add_u32_e32 v1, v69, v85
	s_and_b64 vcc, exec, s[6:7]
	ds_write_b32 v1, v9
	s_cbranch_vccnz .LBB0_499
	s_waitcnt vmcnt(0)
	v_mul_f32_e32 v10, v10, v110
.LBB0_499:
	v_add_u32_e32 v1, v69, v86
	s_and_b64 vcc, exec, s[6:7]
	ds_write_b32 v1, v10
	s_cbranch_vccnz .LBB0_501
	s_waitcnt vmcnt(0)
	v_mul_f32_e32 v11, v11, v111
.LBB0_501:
	v_add_u32_e32 v1, v69, v87
	s_and_b64 vcc, exec, s[6:7]
	ds_write_b32 v1, v11
	s_cbranch_vccnz .LBB0_503
	s_waitcnt vmcnt(0)
	v_mul_f32_e32 v12, v12, v112
.LBB0_503:
	v_add_u32_e32 v1, v69, v88
	s_and_b64 vcc, exec, s[6:7]
	ds_write_b32 v1, v12
	s_cbranch_vccnz .LBB0_505
	s_waitcnt vmcnt(0)
	v_mul_f32_e32 v13, v13, v113
.LBB0_505:
	v_add_u32_e32 v1, v69, v89
	s_and_b64 vcc, exec, s[6:7]
	ds_write_b32 v1, v13
	s_cbranch_vccnz .LBB0_507
	s_waitcnt vmcnt(0)
	v_mul_f32_e32 v14, v14, v114
.LBB0_507:
	v_add_u32_e32 v1, v69, v90
	s_and_b64 vcc, exec, s[6:7]
	ds_write_b32 v1, v14
	s_cbranch_vccnz .LBB0_509
	s_waitcnt vmcnt(0)
	v_mul_f32_e32 v15, v15, v115
.LBB0_509:
	s_and_b64 vcc, exec, s[6:7]
	ds_write_b32 v1, v15 offset:264
	s_cbranch_vccnz .LBB0_511
	s_waitcnt vmcnt(0)
	v_mul_f32_e32 v16, v16, v116
.LBB0_511:
	s_and_b64 vcc, exec, s[6:7]
	ds_write_b32 v1, v16 offset:528
	s_cbranch_vccnz .LBB0_513
	s_waitcnt vmcnt(0)
	v_mul_f32_e32 v17, v17, v117
.LBB0_513:
	s_and_b64 vcc, exec, s[6:7]
	ds_write_b32 v1, v17 offset:792
	s_cbranch_vccnz .LBB0_515
	s_waitcnt vmcnt(0)
	v_mul_f32_e32 v18, v18, v118
.LBB0_515:
	s_and_b64 vcc, exec, s[6:7]
	ds_write_b32 v1, v18 offset:1056
	s_cbranch_vccnz .LBB0_517
	s_waitcnt vmcnt(0)
	v_mul_f32_e32 v19, v19, v119
.LBB0_517:
	s_and_b64 vcc, exec, s[6:7]
	ds_write_b32 v1, v19 offset:1320
	s_cbranch_vccnz .LBB0_519
	s_waitcnt vmcnt(0)
	v_mul_f32_e32 v20, v20, v120
.LBB0_519:
	s_and_b64 vcc, exec, s[6:7]
	ds_write_b32 v1, v20 offset:1584
	s_cbranch_vccnz .LBB0_521
	s_waitcnt vmcnt(0)
	v_mul_f32_e32 v21, v21, v121
.LBB0_521:
	s_and_b64 vcc, exec, s[6:7]
	ds_write_b32 v1, v21 offset:1848
	s_cbranch_vccnz .LBB0_523
	s_waitcnt vmcnt(0)
	v_mul_f32_e32 v22, v22, v122
.LBB0_523:
	s_and_b64 vcc, exec, s[6:7]
	ds_write_b32 v1, v22 offset:2112
	s_cbranch_vccnz .LBB0_525
	s_waitcnt vmcnt(0)
	v_mul_f32_e32 v23, v23, v123
.LBB0_525:
	s_and_b64 vcc, exec, s[6:7]
	ds_write_b32 v1, v23 offset:2376
	s_cbranch_vccnz .LBB0_527
	s_waitcnt vmcnt(0)
	v_mul_f32_e32 v24, v24, v124
.LBB0_527:
	s_and_b64 vcc, exec, s[6:7]
	ds_write_b32 v1, v24 offset:2640
	s_cbranch_vccnz .LBB0_529
	s_waitcnt vmcnt(0)
	v_mul_f32_e32 v25, v25, v125
.LBB0_529:
	s_and_b64 vcc, exec, s[6:7]
	ds_write_b32 v1, v25 offset:2904
	s_cbranch_vccnz .LBB0_531
	s_waitcnt vmcnt(0)
	v_mul_f32_e32 v26, v26, v126
.LBB0_531:
	s_and_b64 vcc, exec, s[6:7]
	ds_write_b32 v1, v26 offset:3168
	s_cbranch_vccnz .LBB0_533
	s_waitcnt vmcnt(0)
	v_mul_f32_e32 v27, v27, v127
.LBB0_533:
	s_and_b64 vcc, exec, s[6:7]
	ds_write_b32 v1, v27 offset:3432
	s_cbranch_vccnz .LBB0_535
	s_waitcnt vmcnt(0)
	v_mul_f32_e32 v28, v28, v128
.LBB0_535:
	s_and_b64 vcc, exec, s[6:7]
	ds_write_b32 v1, v28 offset:3696
	s_cbranch_vccnz .LBB0_537
	s_waitcnt vmcnt(0)
	v_mul_f32_e32 v29, v29, v129
.LBB0_537:
	s_and_b64 vcc, exec, s[6:7]
	ds_write_b32 v1, v29 offset:3960
	s_cbranch_vccnz .LBB0_539
	s_waitcnt vmcnt(0)
	v_mul_f32_e32 v30, v30, v130
.LBB0_539:
	s_and_b64 vcc, exec, s[6:7]
	ds_write_b32 v1, v30 offset:4224
	s_cbranch_vccnz .LBB0_541
	s_waitcnt vmcnt(0)
	v_mul_f32_e32 v31, v31, v131

.LBB0_550:
	s_mul_i32 s7, s14, 0x6000000
	s_mul_hi_i32 s6, s14, 0x6000000
	s_add_u32 s19, s60, s7
	s_addc_u32 s31, s61, s6
	s_lshl_b32 s6, s14, 11
	s_ashr_i32 s7, s6, 31
	s_lshl_b64 s[6:7], s[6:7], 2
	s_add_u32 s20, s58, s6
	s_mul_hi_i32 s6, s18, 0x2aaaaaab
	s_addc_u32 s21, s59, s7
	s_lshr_b32 s7, s6, 31
	s_ashr_i32 s6, s6, 6
	s_add_i32 s6, s6, s7
	s_mul_i32 s15, s14, 0x8200
	s_mul_i32 s7, s6, 0xfffffe80
	s_sub_i32 s7, s7, s15
	s_add_i32 s7, s30, s7
	s_lshl_b32 s16, s7, 5
	s_ashr_i32 s17, s16, 31
	s_lshl_b32 s18, s6, 6
	s_lshl_b64 s[6:7], s[16:17], 2
	v_or_b32_e32 v32, s18, v66
	s_add_u32 s6, s19, s6
	s_addc_u32 s7, s31, s7
	v_lshlrev_b32_e32 v64, 2, v68
	v_mul_lo_u32 v4, v32, s33
	v_lshl_add_u64 v[2:3], s[6:7], 0, v[64:65]
	v_ashrrev_i32_e32 v5, 31, v4
	v_lshl_add_u64 v[34:35], v[4:5], 2, v[2:3]
	v_mad_i64_i32 v[0:1], s[6:7], v32, s42, v[2:3]
	v_add_co_u32_e32 v2, vcc, s39, v34
	global_load_dword v0, v[0:1], off
	s_nop 0
	v_addc_co_u32_e32 v3, vcc, 0, v35, vcc
	global_load_dword v1, v[2:3], off
	v_add_co_u32_e32 v2, vcc, s43, v34
	s_mov_b32 s6, 0x78000
	s_nop 0
	v_addc_co_u32_e32 v3, vcc, 0, v35, vcc
	v_add_co_u32_e32 v4, vcc, s55, v34
	global_load_dword v2, v[2:3], off
	s_nop 0
	v_addc_co_u32_e32 v5, vcc, 0, v35, vcc
	global_load_dword v3, v[4:5], off
	v_add_co_u32_e32 v4, vcc, s44, v34
	v_cndmask_b32_e64 v33, 0, 1, s[12:13]
	s_nop 0
	v_addc_co_u32_e32 v5, vcc, 0, v35, vcc
	v_add_co_u32_e32 v6, vcc, s6, v34
	s_mov_b32 s6, 0x90000
	s_nop 0
	v_addc_co_u32_e32 v7, vcc, 0, v35, vcc
	global_load_dword v4, v[4:5], off
	s_nop 0
	global_load_dword v5, v[6:7], off
	v_add_co_u32_e32 v6, vcc, s6, v34
	s_mov_b32 s6, 0xa8000
	s_nop 0
	v_addc_co_u32_e32 v7, vcc, 0, v35, vcc
	v_add_co_u32_e32 v8, vcc, s6, v34
	s_mov_b32 s6, 0xc0000
	s_nop 0
	v_addc_co_u32_e32 v9, vcc, 0, v35, vcc
	global_load_dword v6, v[6:7], off
	s_nop 0
	global_load_dword v7, v[8:9], off
	v_add_co_u32_e32 v8, vcc, s6, v34
	s_mov_b32 s6, 0xd8000
	s_nop 0
	v_addc_co_u32_e32 v9, vcc, 0, v35, vcc
	v_add_co_u32_e32 v10, vcc, s6, v34
	s_mov_b32 s6, 0xf0000
	s_nop 0
	v_addc_co_u32_e32 v11, vcc, 0, v35, vcc
	global_load_dword v8, v[8:9], off
	s_nop 0
	global_load_dword v9, v[10:11], off
	v_add_co_u32_e32 v10, vcc, s6, v34
	s_mov_b32 s6, 0x108000
	s_nop 0
	v_addc_co_u32_e32 v11, vcc, 0, v35, vcc
	v_add_co_u32_e32 v12, vcc, s6, v34
	s_mov_b32 s6, 0x120000
	s_nop 0
	v_addc_co_u32_e32 v13, vcc, 0, v35, vcc
	global_load_dword v10, v[10:11], off
	s_nop 0
	global_load_dword v11, v[12:13], off
	v_add_co_u32_e32 v12, vcc, s6, v34
	s_mov_b32 s6, 0x138000
	s_nop 0
	v_addc_co_u32_e32 v13, vcc, 0, v35, vcc
	v_add_co_u32_e32 v14, vcc, s6, v34
	s_mov_b32 s6, 0x150000
	s_nop 0
	v_addc_co_u32_e32 v15, vcc, 0, v35, vcc
	global_load_dword v12, v[12:13], off
	s_nop 0
	global_load_dword v13, v[14:15], off
	v_add_co_u32_e32 v14, vcc, s6, v34
	s_mov_b32 s6, 0x168000
	s_nop 0
	v_addc_co_u32_e32 v15, vcc, 0, v35, vcc
	v_add_co_u32_e32 v16, vcc, s6, v34
	s_mov_b32 s6, 0x180000
	s_nop 0
	v_addc_co_u32_e32 v17, vcc, 0, v35, vcc
	global_load_dword v14, v[14:15], off
	s_nop 0
	global_load_dword v15, v[16:17], off
	v_add_co_u32_e32 v16, vcc, s6, v34
	s_mov_b32 s6, 0x198000
	s_nop 0
	v_addc_co_u32_e32 v17, vcc, 0, v35, vcc
	v_add_co_u32_e32 v18, vcc, s6, v34
	s_mov_b32 s6, 0x1b0000
	s_nop 0
	v_addc_co_u32_e32 v19, vcc, 0, v35, vcc
	global_load_dword v16, v[16:17], off
	s_nop 0
	global_load_dword v17, v[18:19], off
	v_add_co_u32_e32 v18, vcc, s6, v34
	s_mov_b32 s6, 0x1c8000
	s_nop 0
	v_addc_co_u32_e32 v19, vcc, 0, v35, vcc
	v_add_co_u32_e32 v20, vcc, s6, v34
	s_mov_b32 s6, 0x1e0000
	s_nop 0
	v_addc_co_u32_e32 v21, vcc, 0, v35, vcc
	global_load_dword v18, v[18:19], off
	s_nop 0
	global_load_dword v19, v[20:21], off
	v_add_co_u32_e32 v20, vcc, s6, v34
	s_mov_b32 s6, 0x1f8000
	s_nop 0
	v_addc_co_u32_e32 v21, vcc, 0, v35, vcc
	v_add_co_u32_e32 v22, vcc, s6, v34
	global_load_dword v20, v[20:21], off
	s_nop 0
	v_addc_co_u32_e32 v23, vcc, 0, v35, vcc
	global_load_dword v21, v[22:23], off
	v_add_co_u32_e32 v22, vcc, s45, v34
	s_mov_b32 s6, 0x228000
	s_nop 0
	v_addc_co_u32_e32 v23, vcc, 0, v35, vcc
	v_add_co_u32_e32 v24, vcc, s6, v34
	s_mov_b32 s6, 0x240000
	s_nop 0
	v_addc_co_u32_e32 v25, vcc, 0, v35, vcc
	global_load_dword v22, v[22:23], off
	s_nop 0
	global_load_dword v23, v[24:25], off
	v_add_co_u32_e32 v24, vcc, s6, v34
	s_mov_b32 s6, 0x258000
	s_nop 0
	v_addc_co_u32_e32 v25, vcc, 0, v35, vcc
	v_add_co_u32_e32 v26, vcc, s6, v34
	s_mov_b32 s6, 0x270000
	s_nop 0
	v_addc_co_u32_e32 v27, vcc, 0, v35, vcc
	global_load_dword v24, v[24:25], off
	s_nop 0
	global_load_dword v25, v[26:27], off
	v_add_co_u32_e32 v26, vcc, s6, v34
	s_mov_b32 s6, 0x288000
	s_nop 0
	v_addc_co_u32_e32 v27, vcc, 0, v35, vcc
	v_add_co_u32_e32 v28, vcc, s6, v34
	s_mov_b32 s6, 0x2a0000
	s_nop 0
	v_addc_co_u32_e32 v29, vcc, 0, v35, vcc
	global_load_dword v26, v[26:27], off
	s_nop 0
	global_load_dword v27, v[28:29], off
	v_add_co_u32_e32 v28, vcc, s6, v34
	v_cmp_ne_u32_e64 s[6:7], 1, v33
	s_nop 0
	v_addc_co_u32_e32 v29, vcc, 0, v35, vcc
	v_add_co_u32_e32 v30, vcc, 0x2b8000, v34
	global_load_dword v28, v[28:29], off
	s_nop 0
	v_addc_co_u32_e32 v31, vcc, 0, v35, vcc
	global_load_dword v29, v[30:31], off
	v_add_co_u32_e32 v30, vcc, 0x2d0000, v34
	s_nop 1
	v_addc_co_u32_e32 v31, vcc, 0, v35, vcc
	v_add_co_u32_e32 v34, vcc, 0x2e8000, v34
	global_load_dword v30, v[30:31], off
	s_nop 0
	v_addc_co_u32_e32 v35, vcc, 0, v35, vcc
	global_load_dword v31, v[34:35], off
	s_andn2_b64 vcc, exec, s[12:13]
	s_cbranch_vccnz .Lgkpf_skip_in
	s_ashr_i32 s19, s18, 31
	v_lshl_add_u64 v[132:133], s[18:19], 0, v[66:67]
	v_lshl_add_u64 v[132:133], v[132:133], 2, s[20:21]
	global_load_dword v100, v[132:133], off
	global_load_dword v101, v[132:133], off offset:8
	global_load_dword v102, v[132:133], off offset:16
	global_load_dword v103, v[132:133], off offset:24
	global_load_dword v104, v[132:133], off offset:32
	global_load_dword v105, v[132:133], off offset:40
	global_load_dword v106, v[132:133], off offset:48
	global_load_dword v107, v[132:133], off offset:56
	global_load_dword v108, v[132:133], off offset:64
	global_load_dword v109, v[132:133], off offset:72
	global_load_dword v110, v[132:133], off offset:80
	global_load_dword v111, v[132:133], off offset:88
	global_load_dword v112, v[132:133], off offset:96
	global_load_dword v113, v[132:133], off offset:104
	global_load_dword v114, v[132:133], off offset:112
	global_load_dword v115, v[132:133], off offset:120
	global_load_dword v116, v[132:133], off offset:128
	global_load_dword v117, v[132:133], off offset:136
	global_load_dword v118, v[132:133], off offset:144
	global_load_dword v119, v[132:133], off offset:152
	global_load_dword v120, v[132:133], off offset:160
	global_load_dword v121, v[132:133], off offset:168
	global_load_dword v122, v[132:133], off offset:176
	global_load_dword v123, v[132:133], off offset:184
	global_load_dword v124, v[132:133], off offset:192
	global_load_dword v125, v[132:133], off offset:200
	global_load_dword v126, v[132:133], off offset:208
	global_load_dword v127, v[132:133], off offset:216
	global_load_dword v128, v[132:133], off offset:224
	global_load_dword v129, v[132:133], off offset:232
	global_load_dword v130, v[132:133], off offset:240
	global_load_dword v131, v[132:133], off offset:248
.Lgkpf_skip_in:
	s_andn2_b64 vcc, exec, s[12:13]
	s_cbranch_vccnz .LBB0_552
	s_waitcnt vmcnt(0)
	v_mul_f32_e32 v0, v0, v100
.LBB0_552:
	s_and_b64 vcc, exec, s[6:7]
	s_waitcnt vmcnt(0)
	ds_write_b32 v71, v0
	s_cbranch_vccnz .LBB0_554
	s_waitcnt vmcnt(0)
	v_mul_f32_e32 v1, v1, v101

.LBB0_556:
	v_add_u32_e32 v32, v69, v78
	s_and_b64 vcc, exec, s[6:7]
	ds_write_b32 v32, v2
	s_cbranch_vccnz .LBB0_558
	s_waitcnt vmcnt(0)
	v_mul_f32_e32 v3, v3, v103
.LBB0_558:
	v_add_u32_e32 v32, v69, v79
	s_and_b64 vcc, exec, s[6:7]
	ds_write_b32 v32, v3
	s_cbranch_vccnz .LBB0_560
	s_waitcnt vmcnt(0)
	v_mul_f32_e32 v4, v4, v104
.LBB0_560:
	v_add_u32_e32 v32, v69, v80
	s_and_b64 vcc, exec, s[6:7]
	ds_write_b32 v32, v4
	s_cbranch_vccnz .LBB0_562
	s_waitcnt vmcnt(0)
	v_mul_f32_e32 v5, v5, v105
.LBB0_562:
	v_add_u32_e32 v32, v69, v81
	s_and_b64 vcc, exec, s[6:7]
	ds_write_b32 v32, v5
	s_cbranch_vccnz .LBB0_564
	s_waitcnt vmcnt(0)
	v_mul_f32_e32 v6, v6, v106
.LBB0_564:
	v_add_u32_e32 v32, v69, v82
	s_and_b64 vcc, exec, s[6:7]
	ds_write_b32 v32, v6
	s_cbranch_vccnz .LBB0_566
	s_waitcnt vmcnt(0)
	v_mul_f32_e32 v7, v7, v107
.LBB0_566:
	v_add_u32_e32 v32, v69, v83
	s_and_b64 vcc, exec, s[6:7]
	ds_write_b32 v32, v7
	s_cbranch_vccnz .LBB0_568
	s_waitcnt vmcnt(0)
	v_mul_f32_e32 v8, v8, v108
.LBB0_568:
	v_add_u32_e32 v32, v69, v84
	s_and_b64 vcc, exec, s[6:7]
	ds_write_b32 v32, v8
	s_cbranch_vccnz .LBB0_570
	s_waitcnt vmcnt(0)
	v_mul_f32_e32 v9, v9, v109
.LBB0_570:
	v_add_u32_e32 v32, v69, v85
	s_and_b64 vcc, exec, s[6:7]
	ds_write_b32 v32, v9
	s_cbranch_vccnz .LBB0_572
	s_waitcnt vmcnt(0)
	v_mul_f32_e32 v10, v10, v110
.LBB0_572:
	v_add_u32_e32 v32, v69, v86
	s_and_b64 vcc, exec, s[6:7]
	ds_write_b32 v32, v10
	s_cbranch_vccnz .LBB0_574
	s_waitcnt vmcnt(0)
	v_mul_f32_e32 v11, v11, v111
.LBB0_574:
	v_add_u32_e32 v32, v69, v87
	s_and_b64 vcc, exec, s[6:7]
	ds_write_b32 v32, v11
	s_cbranch_vccnz .LBB0_576
	s_waitcnt vmcnt(0)
	v_mul_f32_e32 v12, v12, v112
.LBB0_576:
	v_add_u32_e32 v32, v69, v88
	s_and_b64 vcc, exec, s[6:7]
	ds_write_b32 v32, v12
	s_cbranch_vccnz .LBB0_578
	s_waitcnt vmcnt(0)
	v_mul_f32_e32 v13, v13, v113
.LBB0_578:
	v_add_u32_e32 v32, v69, v89
	s_and_b64 vcc, exec, s[6:7]
	ds_write_b32 v32, v13
	s_cbranch_vccnz .LBB0_580
	s_waitcnt vmcnt(0)
	v_mul_f32_e32 v14, v14, v114
.LBB0_580:
	v_add_u32_e32 v64, v69, v90
	s_and_b64 vcc, exec, s[6:7]
	ds_write_b32 v64, v14
	s_cbranch_vccnz .LBB0_582
	s_waitcnt vmcnt(0)
	v_mul_f32_e32 v15, v15, v115
.LBB0_582:
	s_and_b64 vcc, exec, s[6:7]
	ds_write_b32 v64, v15 offset:264
	s_cbranch_vccnz .LBB0_584
	s_waitcnt vmcnt(0)
	v_mul_f32_e32 v16, v16, v116
.LBB0_584:
	s_and_b64 vcc, exec, s[6:7]
	ds_write_b32 v64, v16 offset:528
	s_cbranch_vccnz .LBB0_586
	s_waitcnt vmcnt(0)
	v_mul_f32_e32 v17, v17, v117
.LBB0_586:
	s_and_b64 vcc, exec, s[6:7]
	ds_write_b32 v64, v17 offset:792
	s_cbranch_vccnz .LBB0_588
	s_waitcnt vmcnt(0)
	v_mul_f32_e32 v18, v18, v118
.LBB0_588:
	s_and_b64 vcc, exec, s[6:7]
	ds_write_b32 v64, v18 offset:1056
	s_cbranch_vccnz .LBB0_590
	s_waitcnt vmcnt(0)
	v_mul_f32_e32 v19, v19, v119
.LBB0_590:
	s_and_b64 vcc, exec, s[6:7]
	ds_write_b32 v64, v19 offset:1320
	s_cbranch_vccnz .LBB0_592
	s_waitcnt vmcnt(0)
	v_mul_f32_e32 v20, v20, v120
.LBB0_592:
	s_and_b64 vcc, exec, s[6:7]
	ds_write_b32 v64, v20 offset:1584
	s_cbranch_vccnz .LBB0_594
	s_waitcnt vmcnt(0)
	v_mul_f32_e32 v21, v21, v121
.LBB0_594:
	s_and_b64 vcc, exec, s[6:7]
	ds_write_b32 v64, v21 offset:1848
	s_cbranch_vccnz .LBB0_596
	s_waitcnt vmcnt(0)
	v_mul_f32_e32 v22, v22, v122
.LBB0_596:
	s_and_b64 vcc, exec, s[6:7]
	ds_write_b32 v64, v22 offset:2112
	s_cbranch_vccnz .LBB0_598
	s_waitcnt vmcnt(0)
	v_mul_f32_e32 v23, v23, v123
.LBB0_598:
	s_and_b64 vcc, exec, s[6:7]
	ds_write_b32 v64, v23 offset:2376
	s_cbranch_vccnz .LBB0_600
	s_waitcnt vmcnt(0)
	v_mul_f32_e32 v24, v24, v124
.LBB0_600:
	s_and_b64 vcc, exec, s[6:7]
	ds_write_b32 v64, v24 offset:2640
	s_cbranch_vccnz .LBB0_602
	s_waitcnt vmcnt(0)
	v_mul_f32_e32 v25, v25, v125
.LBB0_602:
	s_and_b64 vcc, exec, s[6:7]
	ds_write_b32 v64, v25 offset:2904
	s_cbranch_vccnz .LBB0_604
	s_waitcnt vmcnt(0)
	v_mul_f32_e32 v26, v26, v126
.LBB0_604:
	s_and_b64 vcc, exec, s[6:7]
	ds_write_b32 v64, v26 offset:3168
	s_cbranch_vccnz .LBB0_606
	s_waitcnt vmcnt(0)
	v_mul_f32_e32 v27, v27, v127
.LBB0_606:
	s_and_b64 vcc, exec, s[6:7]
	ds_write_b32 v64, v27 offset:3432
	s_cbranch_vccnz .LBB0_608
	s_waitcnt vmcnt(0)
	v_mul_f32_e32 v28, v28, v128
.LBB0_608:
	s_and_b64 vcc, exec, s[6:7]
	ds_write_b32 v64, v28 offset:3696
	s_cbranch_vccnz .LBB0_610
	s_waitcnt vmcnt(0)
	v_mul_f32_e32 v29, v29, v129
.LBB0_610:
	s_and_b64 vcc, exec, s[6:7]
	ds_write_b32 v64, v29 offset:3960
	s_cbranch_vccnz .LBB0_612
	s_waitcnt vmcnt(0)
	v_mul_f32_e32 v30, v30, v130
.LBB0_612:
	s_and_b64 vcc, exec, s[12:13]
	ds_write_b32 v64, v30 offset:4224
	s_cbranch_vccz .LBB0_614
	s_waitcnt vmcnt(0)
	v_mul_f32_e32 v63, v31, v131
	s_cbranch_execnz .LBB0_469
	s_branch .LBB0_468
